# barrier v2: workgroups poll the cross-XCC counter directly, L1 invalidate issued at arrival
# speedup vs baseline: 1.0447x; 1.0447x over previous
; __global__ void __launch_bounds__(NT) fwd_kernel(Params P) {
;     ...
;   for (int ph = P.ph_lo; ph < P.ph_hi; ++ph) {
;     if (ph > P.ph_lo) grid.sync();
.Lxb_c2:
	global_load_dword v2, v65, s[4:5] offset:4 sc1
	s_waitcnt vmcnt(0)
	v_readfirstlane_b32 s9, v2
	s_cmp_ge_u32 s9, s7
	s_cbranch_scc1 .Lxb_c3
	s_sleep 1
	s_add_i32 s10, s10, 1
	s_cmp_lt_u32 s10, 0x8000
	s_cbranch_scc1 .Lxb_c2

; __global__ void __launch_bounds__(NT) fwd_kernel(Params P) {
;     ...
;   for (int ph = P.ph_lo; ph < P.ph_hi; ++ph) {
;     if (ph > P.ph_lo) grid.sync();
.Lxb_fast:
	global_atomic_add v2, v0, v1, s[4:5] offset:128 sc0
	buffer_inv sc1
	s_mul_i32 s7, s100, s98
	s_add_i32 s8, s100, -1
	s_mul_i32 s8, s8, s99
	s_mov_b32 s10, 0
	s_waitcnt vmcnt(0)
	v_readfirstlane_b32 s9, v2
	s_add_i32 s9, s9, 1
	s_cmp_lg_u32 s9, s7
	s_cbranch_scc1 .Lxb_wait
	buffer_wbl2 sc1
	s_waitcnt vmcnt(0)
	global_atomic_add v65, v1, s[4:5]
.Lxb_wait:
	global_load_dword v2, v65, s[4:5] sc1
	s_waitcnt vmcnt(0)
	v_readfirstlane_b32 s9, v2
	s_cmp_ge_u32 s9, s8
	s_cbranch_scc1 .Lxb_join
	s_sleep 1
	s_add_i32 s10, s10, 1
	s_cmp_lt_u32 s10, 0x8000
	s_cbranch_scc1 .Lxb_wait
